# attention loop: 16 dead v_mov 0 zero-inits (registers fully rewritten by the two cvt_pk_fp8 halves) removed
# speedup vs baseline: 1.0034x; 1.0005x over previous
; #define SBAR() __builtin_amdgcn_sched_barrier(0)
; __device__ __forceinline__ unsigned pk4f8(float a, float b, float c, float d) { unsigned w = 0u; w = __builtin_amdgcn_cvt_pk_fp8_f32(a, b, w, false); w = __builtin_amdgcn_cvt_pk_fp8_f32(c, d, w, true); return w; }
; #define SLOAD8(i, t) do { sk[i] = *reinterpret_cast<const i32x4a*>(kg + (long)(t) * (64 * 512)); sv[i] = *reinterpret_cast<const i32x4a*>(vg + (long)(t) * VT_STRIDE); } while (0)
; #define SWAIT8() asm volatile("s_waitcnt vmcnt(2)" ::: "memory")
; #define SWRITE8R(boff, i) do { *reinterpret_cast<ATT_LAS i32x4a*>(K_lds + (boff) + kst) = sk[i]; *reinterpret_cast<ATT_LAS i32x4a*>(V_lds + (boff) + vst) = sv[i]; } while (0)
; __device__ __forceinline__ void finishSM8(f32x16& p0, f32x16& p1, float alpha, float& l_reg, i32x8a& pa) {
; #pragma unroll
;   for (int r = 0; r < 16; ++r) p1[r] = __builtin_amdgcn_exp2f(p1[r]);
;   float ps = 0;
; #pragma unroll
;   for (int r = 0; r < 16; ++r) ps += p0[r];
; #pragma unroll
;   for (int r = 0; r < 16; ++r) ps += p1[r];
;   { auto rr = __builtin_amdgcn_permlane32_swap(__float_as_uint(ps), __float_as_uint(ps), false, false);
;     ps = __uint_as_float(rr[0]) + __uint_as_float(rr[1]); }
;   l_reg = l_reg * alpha + ps;
;   pa = (i32x8a){(int)pk4f8(p0[0], p0[1], p0[2], p0[3]), (int)pk4f8(p0[4], p0[5], p0[6], p0[7]), (int)pk4f8(p0[8], p0[9], p0[10], p0[11]), (int)pk4f8(p0[12], p0[13], p0[14], p0[15]),
;                 (int)pk4f8(p1[0], p1[1], p1[2], p1[3]), (int)pk4f8(p1[4], p1[5], p1[6], p1[7]), (int)pk4f8(p1[8], p1[9], p1[10], p1[11]), (int)pk4f8(p1[12], p1[13], p1[14], p1[15])};
; }
; __device__ __forceinline__ void attn_unit8(const bf16_t* __restrict__ Qb, const unsigned char* __restrict__ K8h, const unsigned char* __restrict__ VT8h, unsigned char* __restrict__ Ob, int seq, ATT_LAS char* lds, ...
;     ...
;     SBAR(); qkt8<false>(pB0, pB1, K_lds + bK, q8, r32, hi, one);
;     finishSM8(pA0, pA1, alA, l_reg, pa); SBAR();
;     SLOAD8(1, j + 2); SBAR();
;     pv8<false>(o, V_lds + bV, pa, r32, hi, one); partialSM8(pB0, pB1, m_reg, mnB, alB);
;     SWAIT8(); SWRITE8R(bW, 0);
;     RESC8(alB); __syncthreads();
.LBB0_549:
	s_mov_b32 s54, s52
	s_mov_b32 s52, s8
	s_add_i32 s26, s53, 0
	v_add3_u32 v66, s26, v159, v154
	v_add3_u32 v67, s26, v160, v154
	ds_read_b128 v[188:191], v66 offset:24576
	ds_read_b128 v[210:213], v66 offset:28672
	ds_read_b128 v[192:195], v67 offset:24576
	ds_read_b128 v[214:217], v67 offset:28672
	v_add3_u32 v66, s26, v161, v154
	v_add3_u32 v67, s26, v162, v154
	ds_read_b128 v[218:221], v66 offset:24576
	ds_read_b128 v[226:229], v66 offset:28672
	ds_read_b128 v[222:225], v67 offset:24576
	ds_read_b128 v[230:233], v67 offset:28672
	s_nop 1
	s_setprio 1
	v_mov_b64_e32 v[80:81], s[50:51]
	v_mov_b64_e32 v[78:79], s[48:49]
	v_mov_b64_e32 v[76:77], s[46:47]
	v_mov_b64_e32 v[74:75], s[44:45]
	v_mov_b64_e32 v[72:73], s[42:43]
	v_mov_b64_e32 v[70:71], s[40:41]
	v_mov_b64_e32 v[68:69], s[38:39]
	v_mov_b64_e32 v[66:67], s[36:37]
	v_mov_b64_e32 v[96:97], v[80:81]
	v_mov_b64_e32 v[94:95], v[78:79]
	v_mov_b64_e32 v[92:93], v[76:77]
	v_mov_b64_e32 v[90:91], v[74:75]
	v_mov_b64_e32 v[88:89], v[72:73]
	v_mov_b64_e32 v[86:87], v[70:71]
	v_mov_b64_e32 v[84:85], v[68:69]
	v_mov_b64_e32 v[82:83], v[66:67]
	s_waitcnt lgkmcnt(5)
	v_mfma_scale_f32_32x32x64_f8f6f4 v[82:97], v[188:195], v[98:105], v[82:97], v133, v133 op_sel_hi:[0,0,0]
	s_waitcnt lgkmcnt(4)
	v_mfma_scale_f32_32x32x64_f8f6f4 v[66:81], v[210:217], v[98:105], v[66:81], v133, v133 op_sel_hi:[0,0,0]
	s_waitcnt lgkmcnt(1)
	v_mfma_scale_f32_32x32x64_f8f6f4 v[82:97], v[218:225], v[106:113], v[82:97], v133, v133 op_sel_hi:[0,0,0]
	s_waitcnt lgkmcnt(0)
	v_mfma_scale_f32_32x32x64_f8f6f4 v[66:81], v[226:233], v[106:113], v[66:81], v133, v133 op_sel_hi:[0,0,0]
	s_setprio 0
	v_exp_f32_e32 v155, v144
	v_add_f32_e32 v144, 0, v176
	v_add_f32_e32 v144, v179, v144
	v_add_f32_e32 v144, v172, v144
	v_add_f32_e32 v144, v173, v144
	v_add_f32_e32 v144, v177, v144
	v_add_f32_e32 v144, v180, v144
	v_add_f32_e32 v144, v174, v144
	v_add_f32_e32 v144, v175, v144
	v_add_f32_e32 v144, v182, v144
	v_add_f32_e32 v144, v184, v144
	v_add_f32_e32 v144, v178, v144
	v_add_f32_e32 v144, v181, v144
	v_exp_f32_e32 v122, v150
	v_add_f32_e32 v144, v185, v144
	v_exp_f32_e32 v123, v151
	v_add_f32_e32 v144, v187, v144
	v_exp_f32_e32 v124, v148
	v_add_f32_e32 v144, v183, v144
	v_exp_f32_e32 v125, v149
	v_add_f32_e32 v144, v186, v144
	v_exp_f32_e32 v150, v146
	v_add_f32_e32 v144, v122, v144
	v_exp_f32_e32 v151, v147
	v_add_f32_e32 v144, v123, v144
	v_add_f32_e32 v144, v124, v144
	v_exp_f32_e32 v156, v145
	v_add_f32_e32 v144, v125, v144
	v_exp_f32_e32 v142, v142
	v_add_f32_e32 v144, v150, v144
	v_exp_f32_e32 v143, v143
	v_add_f32_e32 v144, v151, v144
	v_exp_f32_e32 v140, v140
	v_add_f32_e32 v144, v155, v144
	v_exp_f32_e32 v141, v141
	v_add_f32_e32 v144, v156, v144
	v_exp_f32_e32 v128, v128
	v_add_f32_e32 v144, v142, v144
	v_exp_f32_e32 v129, v129
	v_add_f32_e32 v144, v143, v144
	v_exp_f32_e32 v126, v126
	v_add_f32_e32 v144, v140, v144
	v_exp_f32_e32 v127, v127
	v_add_f32_e32 v144, v141, v144
	v_add_f32_e32 v144, v128, v144
	v_add_f32_e32 v144, v129, v144
	v_add_f32_e32 v144, v126, v144
	v_add_f32_e32 v169, v127, v144
	v_cvt_pk_fp8_f32 v144, v176, v179
	v_cvt_pk_fp8_f32 v149, v150, v151
	v_cvt_pk_fp8_f32 v145, v177, v180
	v_cvt_pk_fp8_f32 v146, v182, v184
	v_cvt_pk_fp8_f32 v147, v185, v187
	v_cvt_pk_fp8_f32 v144, v172, v173 op_sel:[0,0,1]
	v_cvt_pk_fp8_f32 v148, v122, v123
	v_cvt_pk_fp8_f32 v150, v142, v143
	v_cvt_pk_fp8_f32 v151, v128, v129
	v_mov_b32_e32 v170, v169
	s_nop 1
	v_permlane32_swap_b32_e32 v169, v170
	v_cvt_pk_fp8_f32 v145, v174, v175 op_sel:[0,0,1]
	v_cvt_pk_fp8_f32 v146, v178, v181 op_sel:[0,0,1]
	v_cvt_pk_fp8_f32 v147, v183, v186 op_sel:[0,0,1]
	v_cvt_pk_fp8_f32 v148, v124, v125 op_sel:[0,0,1]
	v_cvt_pk_fp8_f32 v149, v155, v156 op_sel:[0,0,1]
	v_cvt_pk_fp8_f32 v150, v140, v141 op_sel:[0,0,1]
	v_cvt_pk_fp8_f32 v151, v126, v127 op_sel:[0,0,1]
	v_lshl_add_u64 v[142:143], s[10:11], 0, v[136:137]
	v_add_co_u32_e32 v122, vcc, s74, v142
	v_lshl_add_u64 v[140:141], s[10:11], 0, v[138:139]
	s_nop 0
	v_addc_co_u32_e32 v123, vcc, 0, v143, vcc
	v_add_co_u32_e32 v126, vcc, s75, v140
	s_nop 1
	v_addc_co_u32_e32 v127, vcc, 0, v141, vcc
	flat_load_dwordx4 v[122:125], v[122:123]
	s_nop 0
	flat_load_dwordx4 v[126:129], v[126:127]
	s_add_i32 s56, s54, 0
	v_add_u32_e32 v155, s56, v164
	v_add_u32_e32 v155, v155, v163
	v_add_u32_e32 v156, s56, v165
	v_add_u32_e32 v156, v156, v163
	ds_read_b128 v[172:175], v155
	ds_read_b128 v[180:183], v155 offset:2048
	ds_read_b128 v[176:179], v156
	ds_read_b128 v[184:187], v156 offset:2048
	ds_read_b128 v[188:191], v155 offset:4096
	ds_read_b128 v[210:213], v155 offset:6144
	ds_read_b128 v[192:195], v156 offset:4096
	ds_read_b128 v[214:217], v156 offset:6144
	s_setprio 1
	s_waitcnt lgkmcnt(0)
	v_mfma_scale_f32_32x32x64_f8f6f4 v[2:17], v[144:151], v[172:179], v[2:17], v133, v133 op_sel_hi:[0,0,0]
	v_mfma_scale_f32_32x32x64_f8f6f4 v[50:65], v[144:151], v[180:187], v[50:65], v133, v133 op_sel_hi:[0,0,0]
	v_mfma_scale_f32_32x32x64_f8f6f4 v[34:49], v[144:151], v[188:195], v[34:49], v133, v133 op_sel_hi:[0,0,0]
	v_mfma_scale_f32_32x32x64_f8f6f4 v[18:33], v[144:151], v[210:217], v[18:33], v133, v133 op_sel_hi:[0,0,0]
	s_setprio 0
	v_max_f32_e32 v144, v83, v83
	v_max_f32_e32 v145, v82, v82
	v_max_f32_e32 v144, v145, v144
	v_max3_f32 v144, v144, v84, v85
	v_max3_f32 v144, v144, v86, v87
	v_max3_f32 v144, v144, v88, v89
	v_max3_f32 v144, v144, v90, v91
	v_max3_f32 v144, v144, v92, v93
	v_max3_f32 v144, v144, v94, v95
	v_max3_f32 v144, v144, v96, v97
	v_max3_f32 v144, v144, v66, v67
	v_max3_f32 v144, v144, v68, v69
	v_max3_f32 v144, v144, v70, v71
	v_max3_f32 v144, v144, v72, v73
	v_max3_f32 v144, v144, v74, v75
	v_max3_f32 v144, v144, v76, v77
	v_max3_f32 v144, v144, v78, v79
	v_max3_f32 v144, v144, v80, v81
	v_mov_b32_e32 v145, v144
	s_nop 1
	v_permlane32_swap_b32_e32 v144, v145
	v_max_f32_e32 v145, v145, v145
	v_max_f32_e32 v144, v144, v144
	v_max_f32_e32 v144, v144, v145
	v_max_f32_e32 v146, v167, v167
	v_sub_f32_e32 v145, v144, v167
	v_max_f32_e32 v144, v146, v144
	v_sub_f32_e32 v146, v167, v144
	v_mul_f32_e32 v146, 0x3e0293ee, v146
	v_exp_f32_e32 v146, v146
	v_cmp_ge_f32_e32 vcc, s69, v145
	s_cmp_eq_u64 vcc, exec
	s_cselect_b64 s[8:9], -1, 0
	s_waitcnt vmcnt(2)
	s_add_i32 s55, s52, 0
	v_cndmask_b32_e64 v171, v146, 1.0, s[8:9]
	v_add_u32_e32 v145, s55, v208
	ds_write_b128 v145, v[118:121] offset:24576
	v_add_u32_e32 v145, s52, v158
	v_cmp_gt_f32_e32 vcc, 1.0, v171
	ds_write_b128 v145, v[114:117]
	s_cbranch_vccz .LBB0_553
	s_and_saveexec_b64 s[24:25], s[6:7]
	ds_write_b32 v152, v171 offset:49280
	s_or_b64 exec, exec, s[24:25]
	s_waitcnt lgkmcnt(0)
	v_add_u32_e32 v145, v206, v134
	ds_read_b128 v[146:149], v145 offset:49376
	ds_read_b128 v[172:175], v145 offset:49344
	ds_read_b128 v[176:179], v145 offset:49312
	ds_read_b128 v[180:183], v145 offset:49280
	s_waitcnt lgkmcnt(0)
	v_pk_mul_f32 v[14:15], v[14:15], v[146:147]
	v_pk_mul_f32 v[10:11], v[10:11], v[172:173]
	v_pk_mul_f32 v[6:7], v[6:7], v[176:177]
	v_pk_mul_f32 v[16:17], v[16:17], v[148:149]
	v_pk_mul_f32 v[12:13], v[12:13], v[174:175]
	v_pk_mul_f32 v[8:9], v[8:9], v[178:179]
	v_pk_mul_f32 v[4:5], v[4:5], v[182:183]
	v_pk_mul_f32 v[2:3], v[2:3], v[180:181]
	v_pk_mul_f32 v[62:63], v[62:63], v[146:147]
	v_pk_mul_f32 v[58:59], v[58:59], v[172:173]
	v_pk_mul_f32 v[54:55], v[54:55], v[176:177]
	v_pk_mul_f32 v[64:65], v[64:65], v[148:149]
	v_pk_mul_f32 v[60:61], v[60:61], v[174:175]
	v_pk_mul_f32 v[56:57], v[56:57], v[178:179]
	v_pk_mul_f32 v[52:53], v[52:53], v[182:183]
	v_pk_mul_f32 v[50:51], v[50:51], v[180:181]
	v_pk_mul_f32 v[46:47], v[46:47], v[146:147]
	v_pk_mul_f32 v[42:43], v[42:43], v[172:173]
	v_pk_mul_f32 v[38:39], v[38:39], v[176:177]
	v_pk_mul_f32 v[48:49], v[48:49], v[148:149]
	v_pk_mul_f32 v[44:45], v[44:45], v[174:175]
	v_pk_mul_f32 v[40:41], v[40:41], v[178:179]
	v_pk_mul_f32 v[36:37], v[36:37], v[182:183]
	v_pk_mul_f32 v[34:35], v[34:35], v[180:181]
	v_pk_mul_f32 v[30:31], v[30:31], v[146:147]
	v_pk_mul_f32 v[26:27], v[26:27], v[172:173]
	v_pk_mul_f32 v[22:23], v[22:23], v[176:177]
	v_pk_mul_f32 v[32:33], v[32:33], v[148:149]
	v_pk_mul_f32 v[28:29], v[28:29], v[174:175]
	v_pk_mul_f32 v[24:25], v[24:25], v[178:179]
	v_pk_mul_f32 v[20:21], v[20:21], v[182:183]
	v_pk_mul_f32 v[18:19], v[18:19], v[180:181]

; #define SBAR() __builtin_amdgcn_sched_barrier(0)
; __device__ __forceinline__ unsigned pk4f8(float a, float b, float c, float d) { unsigned w = 0u; w = __builtin_amdgcn_cvt_pk_fp8_f32(a, b, w, false); w = __builtin_amdgcn_cvt_pk_fp8_f32(c, d, w, true); return w; }
; #define SLOAD8(i, t) do { sk[i] = *reinterpret_cast<const i32x4a*>(kg + (long)(t) * (64 * 512)); sv[i] = *reinterpret_cast<const i32x4a*>(vg + (long)(t) * VT_STRIDE); } while (0)
; #define SWAIT8() asm volatile("s_waitcnt vmcnt(2)" ::: "memory")
; #define SWRITE8R(boff, i) do { *reinterpret_cast<ATT_LAS i32x4a*>(K_lds + (boff) + kst) = sk[i]; *reinterpret_cast<ATT_LAS i32x4a*>(V_lds + (boff) + vst) = sv[i]; } while (0)
; __device__ __forceinline__ void finishSM8(f32x16& p0, f32x16& p1, float alpha, float& l_reg, i32x8a& pa) {
; #pragma unroll
;   for (int r = 0; r < 16; ++r) p1[r] = __builtin_amdgcn_exp2f(p1[r]);
;   float ps = 0;
; #pragma unroll
;   for (int r = 0; r < 16; ++r) ps += p0[r];
; #pragma unroll
;   for (int r = 0; r < 16; ++r) ps += p1[r];
;   { auto rr = __builtin_amdgcn_permlane32_swap(__float_as_uint(ps), __float_as_uint(ps), false, false);
;     ps = __uint_as_float(rr[0]) + __uint_as_float(rr[1]); }
;   l_reg = l_reg * alpha + ps;
;   pa = (i32x8a){(int)pk4f8(p0[0], p0[1], p0[2], p0[3]), (int)pk4f8(p0[4], p0[5], p0[6], p0[7]), (int)pk4f8(p0[8], p0[9], p0[10], p0[11]), (int)pk4f8(p0[12], p0[13], p0[14], p0[15]),
;                 (int)pk4f8(p1[0], p1[1], p1[2], p1[3]), (int)pk4f8(p1[4], p1[5], p1[6], p1[7]), (int)pk4f8(p1[8], p1[9], p1[10], p1[11]), (int)pk4f8(p1[12], p1[13], p1[14], p1[15])};
; }
; __device__ __forceinline__ void attn_unit8(const bf16_t* __restrict__ Qb, const unsigned char* __restrict__ K8h, const unsigned char* __restrict__ VT8h, unsigned char* __restrict__ Ob, int seq, ATT_LAS char* lds, ...
;     ...
;     SBAR(); qkt8<false>(pA0, pA1, K_lds + bK, q8, r32, hi, one);
;     finishSM8(pB0, pB1, alB, l_reg, pa); SBAR();
;     if (j + 3 < NT) SLOAD8(0, j + 3); SBAR();
;     pv8<false>(o, V_lds + bV, pa, r32, hi, one); partialSM8(pA0, pA1, m_reg, mnA, alA);
;     SWAIT8(); SWRITE8R(bW, 1);
;     RESC8(alA); __syncthreads();
.LBB0_555:
	v_cvt_pk_fp8_f32 v210, v168, v175
	v_cvt_pk_fp8_f32 v211, v172, v176
	v_cvt_pk_fp8_f32 v212, v173, v177
	v_cvt_pk_fp8_f32 v213, v174, v178
	v_cvt_pk_fp8_f32 v214, v187, v193
	v_cvt_pk_fp8_f32 v215, v190, v194
	v_cvt_pk_fp8_f32 v216, v191, v195
	v_cvt_pk_fp8_f32 v217, v192, v196
	v_cvt_pk_fp8_f32 v210, v145, v146 op_sel:[0,0,1]
	v_cvt_pk_fp8_f32 v211, v147, v148 op_sel:[0,0,1]
	v_cvt_pk_fp8_f32 v212, v149, v150 op_sel:[0,0,1]
	v_cvt_pk_fp8_f32 v213, v151, v167 op_sel:[0,0,1]
	v_cvt_pk_fp8_f32 v214, v179, v180 op_sel:[0,0,1]
	v_cvt_pk_fp8_f32 v215, v181, v182 op_sel:[0,0,1]
	v_cvt_pk_fp8_f32 v216, v183, v184 op_sel:[0,0,1]
	v_cvt_pk_fp8_f32 v217, v185, v186 op_sel:[0,0,1]
	v_add3_u32 v140, s26, v164, v163
	v_add3_u32 v141, s26, v165, v163
	ds_read_b128 v[172:175], v140
	ds_read_b128 v[180:183], v140 offset:2048
	ds_read_b128 v[176:179], v141
	ds_read_b128 v[184:187], v141 offset:2048
	ds_read_b128 v[190:193], v140 offset:4096
	ds_read_b128 v[218:221], v140 offset:6144
	ds_read_b128 v[194:197], v141 offset:4096
	ds_read_b128 v[222:225], v141 offset:6144
	s_setprio 1
	s_waitcnt lgkmcnt(0)
	v_mfma_scale_f32_32x32x64_f8f6f4 v[2:17], v[210:217], v[172:179], v[2:17], v133, v133 op_sel_hi:[0,0,0]
	v_mfma_scale_f32_32x32x64_f8f6f4 v[50:65], v[210:217], v[180:187], v[50:65], v133, v133 op_sel_hi:[0,0,0]
	v_mfma_scale_f32_32x32x64_f8f6f4 v[34:49], v[210:217], v[190:197], v[34:49], v133, v133 op_sel_hi:[0,0,0]
	v_mfma_scale_f32_32x32x64_f8f6f4 v[18:33], v[210:217], v[218:225], v[18:33], v133, v133 op_sel_hi:[0,0,0]
	s_setprio 0
	v_max_f32_e32 v140, v83, v83
	v_max_f32_e32 v141, v82, v82
	v_max_f32_e32 v140, v141, v140
	v_max3_f32 v140, v140, v84, v85
	v_max3_f32 v140, v140, v86, v87
	v_max3_f32 v140, v140, v88, v89
	v_max3_f32 v140, v140, v90, v91
	v_max3_f32 v140, v140, v92, v93
	v_max3_f32 v140, v140, v94, v95
	v_max3_f32 v140, v140, v96, v97
	v_max3_f32 v140, v140, v66, v67
	v_max3_f32 v140, v140, v68, v69
	v_max3_f32 v140, v140, v70, v71
	v_max3_f32 v140, v140, v72, v73
	v_max3_f32 v140, v140, v74, v75
	v_max3_f32 v140, v140, v76, v77
	v_max3_f32 v140, v140, v78, v79
	v_max3_f32 v140, v140, v80, v81
	v_mov_b32_e32 v141, v140
	s_nop 1
	v_permlane32_swap_b32_e32 v140, v141
	v_max_f32_e32 v141, v141, v141
	v_max_f32_e32 v140, v140, v140
	v_max_f32_e32 v140, v140, v141
	v_max_f32_e32 v142, v144, v144
	v_sub_f32_e32 v141, v140, v144
	v_max_f32_e32 v140, v142, v140
	v_sub_f32_e32 v142, v144, v140
	v_mul_f32_e32 v142, 0x3e0293ee, v142
	v_exp_f32_e32 v142, v142
	v_cmp_ge_f32_e32 vcc, s69, v141
	s_cmp_eq_u64 vcc, exec
	s_cselect_b64 s[8:9], -1, 0
	s_waitcnt vmcnt(2)
	v_cndmask_b32_e64 v168, v142, 1.0, s[8:9]
	v_add_u32_e32 v141, s54, v157
	s_waitcnt vmcnt(0)
	ds_write_b128 v141, v[122:125] offset:24576
	v_add_u32_e32 v122, s56, v207
	v_cmp_gt_f32_e32 vcc, 1.0, v168
	ds_write_b128 v122, v[126:129]
	s_cbranch_vccz .LBB0_559
	s_and_saveexec_b64 s[26:27], s[6:7]
	ds_write_b32 v152, v168 offset:49280
	s_or_b64 exec, exec, s[26:27]
	s_waitcnt lgkmcnt(0)
	v_add_u32_e32 v141, v206, v134
	ds_read_b128 v[122:125], v141 offset:49376
	ds_read_b128 v[126:129], v141 offset:49344
	ds_read_b128 v[146:149], v141 offset:49312
	ds_read_b128 v[172:175], v141 offset:49280
	s_waitcnt lgkmcnt(3)
	v_pk_mul_f32 v[14:15], v[14:15], v[122:123]
	s_waitcnt lgkmcnt(2)
	v_pk_mul_f32 v[10:11], v[10:11], v[126:127]
	s_waitcnt lgkmcnt(1)
	v_pk_mul_f32 v[6:7], v[6:7], v[146:147]
	v_pk_mul_f32 v[16:17], v[16:17], v[124:125]
	v_pk_mul_f32 v[12:13], v[12:13], v[128:129]
	v_pk_mul_f32 v[8:9], v[8:9], v[148:149]
	s_waitcnt lgkmcnt(0)
	v_pk_mul_f32 v[4:5], v[4:5], v[174:175]
	v_pk_mul_f32 v[2:3], v[2:3], v[172:173]
	v_pk_mul_f32 v[62:63], v[62:63], v[122:123]
	v_pk_mul_f32 v[58:59], v[58:59], v[126:127]
	v_pk_mul_f32 v[54:55], v[54:55], v[146:147]
	v_pk_mul_f32 v[64:65], v[64:65], v[124:125]
	v_pk_mul_f32 v[60:61], v[60:61], v[128:129]
	v_pk_mul_f32 v[56:57], v[56:57], v[148:149]
	v_pk_mul_f32 v[52:53], v[52:53], v[174:175]
	v_pk_mul_f32 v[50:51], v[50:51], v[172:173]
	v_pk_mul_f32 v[46:47], v[46:47], v[122:123]
	v_pk_mul_f32 v[42:43], v[42:43], v[126:127]
	v_pk_mul_f32 v[38:39], v[38:39], v[146:147]
	v_pk_mul_f32 v[48:49], v[48:49], v[124:125]
	v_pk_mul_f32 v[44:45], v[44:45], v[128:129]
	v_pk_mul_f32 v[40:41], v[40:41], v[148:149]
	v_pk_mul_f32 v[36:37], v[36:37], v[174:175]
	v_pk_mul_f32 v[34:35], v[34:35], v[172:173]
	v_pk_mul_f32 v[30:31], v[30:31], v[122:123]
	v_pk_mul_f32 v[26:27], v[26:27], v[126:127]
	v_pk_mul_f32 v[22:23], v[22:23], v[146:147]
	v_pk_mul_f32 v[32:33], v[32:33], v[124:125]
	v_pk_mul_f32 v[28:29], v[28:29], v[128:129]
	v_pk_mul_f32 v[24:25], v[24:25], v[148:149]
	v_pk_mul_f32 v[20:21], v[20:21], v[174:175]
	v_pk_mul_f32 v[18:19], v[18:19], v[172:173]
